# v8 plus one static s_setprio 1 for waves 4-7 during the attention phase
# baseline (speedup 1.0000x reference)
; #define LAS __attribute__((address_space(3)))
; __device__ __forceinline__ void attn_phase_mla(ArgP ap, LAS unsigned char* lds, int tid, int wid, int lane) {
;     const bf16_t* MQ = (const bf16_t*)((unsigned char*)ap->out + DO_MQ); const bf16_t* MK = (const bf16_t*)((unsigned char*)ap->out + DO_MK); const bf16_t* MVT = (const bf16_t*)((unsigned char*)ap->out + DO_MVT);
;     bf16_t* AO = (bf16_t*)(ap->ws + WS_AO);
;     const int G = gridDim.x, bx = blockIdx.x, v = (G % 8 == 0) ? (bx % 8) * (G / 8) + bx / 8 : bx;
;     const bool fast = (512 % G == 0); const int per = fast ? 512 / G : 0;
;     for (int i = 0; ; ++i) { int u; if (fast) { if (i >= per) break; u = v * per + i; } else { u = bx + i * G; if (u >= 512) break; }
;         const int qb = u & 7, h = (u >> 3) & 7, b = u >> 6;
;         attn_unit<false>(lds, MQ, MK, MVT, AO, nullptr, nullptr, nullptr, 0.f, b, h, qb, tid, wid, lane, true); }
.LBB0_556:
	s_or_b64 exec, exec, s[42:43]
	v_mov_b32_e32 v181, v220
	s_mov_b64 s[14:15], s[0:1]
	s_waitcnt lgkmcnt(0)
	s_barrier
	v_readfirstlane_b32 s98, v220
	s_nop 3
	s_lshr_b32 s98, s98, 6
	s_cmp_ge_u32 s98, 4
	s_cbranch_scc0 .Lprio_skip
	s_setprio 1
.Lprio_skip:
	s_load_dwordx4 s[8:11], s[14:15], 0xe8
	s_and_b32 s14, s44, 7
	s_cmp_eq_u32 s14, 0
	v_readfirstlane_b32 s12, v181
	s_mov_b32 s13, 0
	s_cselect_b64 s[18:19], -1, 0
	s_cmp_lg_u32 s14, 0
	s_mov_b32 s20, s2
	s_cbranch_scc1 .LBB0_558
	s_ashr_i32 s15, s2, 31
	s_lshr_b32 s15, s15, 29
	s_add_i32 s15, s2, s15
	s_and_b32 s20, s15, -8
	s_ashr_i32 s14, s44, 3
	s_sub_i32 s20, s2, s20
	s_mul_i32 s14, s14, s20
	s_ashr_i32 s15, s15, 3
	s_add_i32 s20, s14, s15

; __device__ __forceinline__ void xcd_barrier(const XcdBarrier& b) {
;     asm volatile("s_waitcnt vmcnt(0)" ::: "memory");
;     __syncthreads();
;     if (threadIdx.x == 0) {
;         unsigned* bar = b.bar; asm volatile("" : "+s"(bar));
;         __builtin_amdgcn_s_waitcnt(0);
;         unsigned nloc = b.st[0], nx = b.st[1];
;         if (nloc == 0u) { xcd_barrier_complete(bar, b.x, nloc, nx); b.st[0] = nloc; b.st[1] = nx; }
.LBB0_632:
	s_waitcnt vmcnt(0)
	s_setprio 0
	s_barrier
	s_and_saveexec_b64 s[42:43], s[16:17]
	s_cbranch_execz .LBB0_676
	s_add_i32 s8, 0, 0x20160
	s_mov_b64 s[48:49], s[46:47]
	v_mov_b32_e32 v0, s8
	s_waitcnt vmcnt(0) expcnt(0) lgkmcnt(0)
	ds_read_b32 v2, v0
	s_add_i32 s8, 0, 0x20164
	v_mov_b32_e32 v0, s8
	ds_read_b32 v0, v0
	s_waitcnt lgkmcnt(1)
	v_cmp_ne_u32_e32 vcc, 0, v2
	s_cbranch_vccnz .LBB0_647
	s_add_u32 s10, s48, 0x1000
	s_addc_u32 s11, s49, 0
	s_add_u32 s12, s48, 0x1100
	s_addc_u32 s13, s49, 0
	s_add_u32 s14, s48, 0x1200
	s_addc_u32 s15, s49, 0
	s_add_u32 s18, s48, 0x1300
	s_mul_i32 s28, s45, s33
	s_addc_u32 s19, s49, 0
	s_mul_i32 s28, s28, s44
	s_mov_b32 s29, 1
	s_mov_b64 s[8:9], 0
	s_waitcnt lgkmcnt(0)
	v_mov_b64_e32 v[0:1], s[48:49]
	v_mov_b64_e32 v[2:3], s[10:11]
	v_mov_b64_e32 v[4:5], s[12:13]
	v_mov_b64_e32 v[6:7], s[14:15]
	v_mov_b64_e32 v[8:9], s[18:19]
	s_branch .LBB0_637
